# vAA + sc1 write-through on the bf16 residual-copy (next GEMM A operand) stores in EpiResid P4/P6 only (f32 X stores unchanged)
# baseline (speedup 1.0000x reference)
.LBB0_665:
	s_lshl_b32 s0, s73, 8
	s_add_i32 s0, s0, s67
	v_mbcnt_lo_u32_b32 v128, -1, 0
	v_mbcnt_hi_u32_b32 v128, -1, v128
	s_lshl_b32 s86, s72, 2
	v_and_or_b32 v156, v128, 15, s0
	s_lshl_b32 s0, s72, 8
	v_ashrrev_i32_e32 v129, 1, v128
	s_or_b32 s0, s0, s68
	v_and_b32_e32 v129, -8, v129
	v_add_u32_e32 v154, s0, v129
	v_ashrrev_i32_e32 v155, 31, v154
	v_ashrrev_i32_e32 v157, 31, v156
	v_cmp_gt_u32_e32 vcc, 16, v128
	v_lshl_add_u64 v[158:159], v[154:155], 2, s[46:47]
	v_lshlrev_b64 v[128:129], 12, v[156:157]
	v_lshl_add_u64 v[128:129], v[158:159], 0, v[128:129]
	global_load_dwordx4 v[164:167], v[128:129], off offset:16
	global_load_dwordx4 v[168:171], v[128:129], off
	global_load_dwordx4 v[172:175], v[128:129], off offset:528
	global_load_dwordx4 v[178:181], v[128:129], off offset:512
	v_or_b32_e32 v160, 16, v156
	v_ashrrev_i32_e32 v161, 31, v160
	v_lshlrev_b64 v[128:129], 12, v[160:161]
	v_lshl_add_u64 v[132:133], v[158:159], 0, v[128:129]
	global_load_dwordx4 v[136:139], v[132:133], off offset:16
	global_load_dwordx4 v[140:143], v[132:133], off
	global_load_dwordx4 v[128:131], v[132:133], off offset:528
	s_nop 0
	global_load_dwordx4 v[132:135], v[132:133], off offset:512
	v_lshlrev_b64 v[182:183], 10, v[156:157]
	v_lshl_add_u64 v[182:183], v[182:183], 0, v[154:155]
	s_ashr_i32 s87, s86, 31
	s_waitcnt vmcnt(0)
	v_pk_add_f32 v[122:123], v[122:123], v[166:167]
	v_pk_add_f32 v[126:127], v[126:127], v[170:171]
	v_pk_add_f32 v[124:125], v[124:125], v[168:169]
	v_lshl_add_u64 v[168:169], v[182:183], 2, s[36:37]
	v_pk_add_f32 v[120:121], v[120:121], v[164:165]
	global_store_dwordx4 v[168:169], v[124:127], off
	global_store_dwordx4 v[168:169], v[120:123], off offset:16
	v_cvt_pk_bf16_f32 v164, v124, v125
	v_cvt_pk_bf16_f32 v165, v126, v127
	v_cvt_pk_bf16_f32 v166, v120, v121
	v_lshl_add_u64 v[170:171], v[182:183], 1, s[48:49]
	v_mul_f32_e32 v125, v125, v125
	v_fmac_f32_e32 v125, v124, v124
	v_mul_f32_e32 v124, v127, v127
	v_fmac_f32_e32 v124, v126, v126
	v_mul_f32_e32 v121, v121, v121
	v_add_f32_e32 v124, v125, v124
	v_fmac_f32_e32 v121, v120, v120
	v_add_f32_e32 v120, v124, v121
	v_mul_f32_e32 v121, v123, v123
	v_fmac_f32_e32 v121, v122, v122
	v_pk_add_f32 v[118:119], v[118:119], v[180:181]
	v_pk_add_f32 v[116:117], v[116:117], v[178:179]
	v_cvt_pk_bf16_f32 v167, v122, v123
	global_store_dwordx4 v[170:171], v[164:167], off sc1
	v_add_f32_e32 v124, v121, v120
	v_pk_add_f32 v[114:115], v[114:115], v[174:175]
	v_pk_add_f32 v[112:113], v[112:113], v[172:173]
	global_store_dwordx4 v[168:169], v[116:119], off offset:512
	global_store_dwordx4 v[168:169], v[112:115], off offset:528
	v_cvt_pk_bf16_f32 v120, v116, v117
	v_cvt_pk_bf16_f32 v121, v118, v119
	v_cvt_pk_bf16_f32 v122, v112, v113
	v_cvt_pk_bf16_f32 v123, v114, v115
	s_nop 0
	v_mul_f32_e32 v117, v117, v117
	v_fmac_f32_e32 v117, v116, v116
	v_mul_f32_e32 v116, v119, v119
	v_fmac_f32_e32 v116, v118, v118
	v_mul_f32_e32 v113, v113, v113
	v_add_f32_e32 v116, v117, v116
	v_fmac_f32_e32 v113, v112, v112
	v_add_f32_e32 v112, v116, v113
	v_mul_f32_e32 v113, v115, v115
	v_fmac_f32_e32 v113, v114, v114
	v_add_f32_e32 v112, v113, v112
	v_add_f32_e32 v112, v124, v112
	ds_swizzle_b32 v113, v112 offset:swizzle(SWAP,16)
	global_store_dwordx4 v[170:171], v[120:123], off offset:256 sc1
	s_waitcnt lgkmcnt(0)
	v_add_f32_e32 v112, v112, v113
	v_mov_b32_e32 v113, v112
	v_mov_b32_e32 v114, v112
	s_nop 1
	v_permlane32_swap_b32_e32 v113, v114
	s_and_saveexec_b64 s[0:1], vcc
	s_cbranch_execz .LBB0_667
	v_cmp_eq_u32_e64 s[44:45], v113, v112
	s_lshl_b32 s92, s66, 2
	s_nop 0
	v_cndmask_b32_e64 v113, v113, v114, s[44:45]
	v_add_f32_e32 v114, v112, v113
	v_lshlrev_b64 v[112:113], 6, v[156:157]
	v_lshl_add_u64 v[112:113], s[50:51], 0, v[112:113]
	v_lshl_add_u64 v[112:113], s[86:87], 2, v[112:113]
	v_lshl_add_u64 v[112:113], v[112:113], 0, s[92:93]
	global_store_dword v[112:113], v114, off
.LBB0_667:
	s_or_b64 exec, exec, s[0:1]
	v_lshlrev_b64 v[112:113], 10, v[160:161]
	v_lshl_add_u64 v[116:117], v[112:113], 0, v[154:155]
	v_pk_add_f32 v[110:111], v[110:111], v[142:143]
	v_pk_add_f32 v[108:109], v[108:109], v[140:141]
	v_lshl_add_u64 v[118:119], v[116:117], 2, s[36:37]
	v_pk_add_f32 v[106:107], v[106:107], v[138:139]
	v_pk_add_f32 v[104:105], v[104:105], v[136:137]
	global_store_dwordx4 v[118:119], v[108:111], off
	global_store_dwordx4 v[118:119], v[104:107], off offset:16
	v_cvt_pk_bf16_f32 v112, v108, v109
	v_cvt_pk_bf16_f32 v113, v110, v111
	v_cvt_pk_bf16_f32 v114, v104, v105
	v_lshl_add_u64 v[116:117], v[116:117], 1, s[48:49]
	v_mul_f32_e32 v109, v109, v109
	v_fmac_f32_e32 v109, v108, v108
	v_mul_f32_e32 v108, v111, v111
	v_fmac_f32_e32 v108, v110, v110
	v_mul_f32_e32 v105, v105, v105
	v_add_f32_e32 v108, v109, v108
	v_fmac_f32_e32 v105, v104, v104
	v_add_f32_e32 v104, v108, v105
	v_mul_f32_e32 v105, v107, v107
	v_fmac_f32_e32 v105, v106, v106
	v_pk_add_f32 v[102:103], v[102:103], v[134:135]
	v_pk_add_f32 v[100:101], v[100:101], v[132:133]
	v_cvt_pk_bf16_f32 v115, v106, v107
	global_store_dwordx4 v[116:117], v[112:115], off sc1
	v_add_f32_e32 v105, v105, v104
	v_pk_add_f32 v[98:99], v[98:99], v[130:131]
	v_pk_add_f32 v[96:97], v[96:97], v[128:129]
	global_store_dwordx4 v[118:119], v[100:103], off offset:512
	global_store_dwordx4 v[118:119], v[96:99], off offset:528
	v_cvt_pk_bf16_f32 v104, v100, v101
	s_nop 0
	v_mul_f32_e32 v101, v101, v101
	v_fmac_f32_e32 v101, v100, v100
	v_mul_f32_e32 v100, v103, v103
	v_fmac_f32_e32 v100, v102, v102
	v_add_f32_e32 v100, v101, v100
	v_mul_f32_e32 v101, v97, v97
	v_fmac_f32_e32 v101, v96, v96
	v_add_f32_e32 v100, v100, v101
	v_mul_f32_e32 v101, v99, v99
	v_fmac_f32_e32 v101, v98, v98
	v_add_f32_e32 v100, v101, v100
	v_add_f32_e32 v100, v105, v100
	ds_swizzle_b32 v101, v100 offset:swizzle(SWAP,16)
	v_cvt_pk_bf16_f32 v105, v102, v103
	v_cvt_pk_bf16_f32 v106, v96, v97
	v_cvt_pk_bf16_f32 v107, v98, v99
	global_store_dwordx4 v[116:117], v[104:107], off offset:256 sc1
	s_waitcnt lgkmcnt(0)
	v_add_f32_e32 v96, v100, v101
	v_mov_b32_e32 v97, v96
	v_mov_b32_e32 v98, v96
	s_nop 1
	v_permlane32_swap_b32_e32 v97, v98
	s_and_saveexec_b64 s[0:1], vcc
	s_cbranch_execz .LBB0_669
	v_cmp_eq_u32_e64 s[44:45], v97, v96
	s_lshl_b32 s92, s66, 2
	s_nop 0
	v_cndmask_b32_e64 v97, v97, v98, s[44:45]
	v_add_f32_e32 v98, v96, v97
	v_lshlrev_b64 v[96:97], 6, v[160:161]
	v_lshl_add_u64 v[96:97], s[50:51], 0, v[96:97]
	v_lshl_add_u64 v[96:97], s[86:87], 2, v[96:97]
	v_lshl_add_u64 v[96:97], v[96:97], 0, s[92:93]
	global_store_dword v[96:97], v98, off
.LBB0_669:
	s_or_b64 exec, exec, s[0:1]
	v_or_b32_e32 v114, 32, v156
	v_ashrrev_i32_e32 v115, 31, v114
	v_lshlrev_b64 v[96:97], 12, v[114:115]
	v_lshl_add_u64 v[96:97], v[158:159], 0, v[96:97]
	global_load_dwordx4 v[116:119], v[96:97], off offset:16
	global_load_dwordx4 v[120:123], v[96:97], off
	global_load_dwordx4 v[124:127], v[96:97], off offset:528
	global_load_dwordx4 v[128:131], v[96:97], off offset:512
	v_or_b32_e32 v112, 48, v156
	v_ashrrev_i32_e32 v113, 31, v112
	v_lshlrev_b64 v[96:97], 12, v[112:113]
	v_lshl_add_u64 v[100:101], v[158:159], 0, v[96:97]
	global_load_dwordx4 v[104:107], v[100:101], off offset:16
	global_load_dwordx4 v[108:111], v[100:101], off
	global_load_dwordx4 v[96:99], v[100:101], off offset:528
	s_nop 0
	global_load_dwordx4 v[100:103], v[100:101], off offset:512
	v_lshlrev_b64 v[132:133], 10, v[114:115]
	v_lshl_add_u64 v[132:133], v[132:133], 0, v[154:155]
	s_waitcnt vmcnt(7)
	v_pk_add_f32 v[90:91], v[90:91], v[118:119]
	s_waitcnt vmcnt(6)
	v_pk_add_f32 v[94:95], v[94:95], v[122:123]
	v_pk_add_f32 v[92:93], v[92:93], v[120:121]
	v_lshl_add_u64 v[120:121], v[132:133], 2, s[36:37]
	v_pk_add_f32 v[88:89], v[88:89], v[116:117]
	global_store_dwordx4 v[120:121], v[92:95], off
	global_store_dwordx4 v[120:121], v[88:91], off offset:16
	v_cvt_pk_bf16_f32 v116, v92, v93
	v_cvt_pk_bf16_f32 v117, v94, v95
	v_cvt_pk_bf16_f32 v118, v88, v89
	v_lshl_add_u64 v[122:123], v[132:133], 1, s[48:49]
	v_mul_f32_e32 v93, v93, v93
	v_fmac_f32_e32 v93, v92, v92
	v_mul_f32_e32 v92, v95, v95
	v_fmac_f32_e32 v92, v94, v94
	v_mul_f32_e32 v89, v89, v89
	v_add_f32_e32 v92, v93, v92
	v_fmac_f32_e32 v89, v88, v88
	v_add_f32_e32 v88, v92, v89
	v_mul_f32_e32 v89, v91, v91
	v_fmac_f32_e32 v89, v90, v90
	s_waitcnt vmcnt(6)
	v_pk_add_f32 v[86:87], v[86:87], v[130:131]
	v_pk_add_f32 v[84:85], v[84:85], v[128:129]
	v_cvt_pk_bf16_f32 v119, v90, v91
	global_store_dwordx4 v[122:123], v[116:119], off sc1
	v_add_f32_e32 v92, v89, v88
	v_pk_add_f32 v[82:83], v[82:83], v[126:127]
	v_pk_add_f32 v[80:81], v[80:81], v[124:125]
	global_store_dwordx4 v[120:121], v[84:87], off offset:512
	global_store_dwordx4 v[120:121], v[80:83], off offset:528
	v_cvt_pk_bf16_f32 v88, v84, v85
	v_cvt_pk_bf16_f32 v89, v86, v87
	v_cvt_pk_bf16_f32 v90, v80, v81
	v_cvt_pk_bf16_f32 v91, v82, v83
	s_nop 0
	v_mul_f32_e32 v85, v85, v85
	v_fmac_f32_e32 v85, v84, v84
	v_mul_f32_e32 v84, v87, v87
	v_fmac_f32_e32 v84, v86, v86
	v_mul_f32_e32 v81, v81, v81
	v_add_f32_e32 v84, v85, v84
	v_fmac_f32_e32 v81, v80, v80
	v_add_f32_e32 v80, v84, v81
	v_mul_f32_e32 v81, v83, v83
	v_fmac_f32_e32 v81, v82, v82
	v_add_f32_e32 v80, v81, v80
	v_add_f32_e32 v80, v92, v80
	ds_swizzle_b32 v81, v80 offset:swizzle(SWAP,16)
	global_store_dwordx4 v[122:123], v[88:91], off offset:256 sc1
	s_waitcnt lgkmcnt(0)
	v_add_f32_e32 v80, v80, v81
	v_mov_b32_e32 v81, v80
	v_mov_b32_e32 v82, v80
	s_nop 1
	v_permlane32_swap_b32_e32 v81, v82
	s_and_saveexec_b64 s[0:1], vcc
	s_cbranch_execz .LBB0_671
	v_cmp_eq_u32_e64 s[44:45], v81, v80
	s_lshl_b32 s92, s66, 2
	s_nop 0
	v_cndmask_b32_e64 v81, v81, v82, s[44:45]
	v_add_f32_e32 v82, v80, v81
	v_lshlrev_b64 v[80:81], 6, v[114:115]
	v_lshl_add_u64 v[80:81], s[50:51], 0, v[80:81]
	v_lshl_add_u64 v[80:81], s[86:87], 2, v[80:81]
	v_lshl_add_u64 v[80:81], v[80:81], 0, s[92:93]
	global_store_dword v[80:81], v82, off
.LBB0_671:
	s_or_b64 exec, exec, s[0:1]
	v_lshlrev_b64 v[80:81], 10, v[112:113]
	v_lshl_add_u64 v[84:85], v[80:81], 0, v[154:155]
	s_waitcnt vmcnt(8)
	v_pk_add_f32 v[78:79], v[78:79], v[110:111]
	v_pk_add_f32 v[76:77], v[76:77], v[108:109]
	v_lshl_add_u64 v[86:87], v[84:85], 2, s[36:37]
	v_pk_add_f32 v[74:75], v[74:75], v[106:107]
	v_pk_add_f32 v[72:73], v[72:73], v[104:105]
	global_store_dwordx4 v[86:87], v[76:79], off
	global_store_dwordx4 v[86:87], v[72:75], off offset:16
	v_cvt_pk_bf16_f32 v80, v76, v77
	v_cvt_pk_bf16_f32 v81, v78, v79
	v_cvt_pk_bf16_f32 v82, v72, v73
	v_lshl_add_u64 v[84:85], v[84:85], 1, s[48:49]
	v_mul_f32_e32 v77, v77, v77
	v_fmac_f32_e32 v77, v76, v76
	v_mul_f32_e32 v76, v79, v79
	v_fmac_f32_e32 v76, v78, v78
	v_mul_f32_e32 v73, v73, v73
	v_add_f32_e32 v76, v77, v76
	v_fmac_f32_e32 v73, v72, v72
	v_add_f32_e32 v72, v76, v73
	v_mul_f32_e32 v73, v75, v75
	v_fmac_f32_e32 v73, v74, v74
	s_waitcnt vmcnt(8)
	v_pk_add_f32 v[70:71], v[70:71], v[102:103]
	v_pk_add_f32 v[68:69], v[68:69], v[100:101]
	v_cvt_pk_bf16_f32 v83, v74, v75
	global_store_dwordx4 v[84:85], v[80:83], off sc1
	v_add_f32_e32 v73, v73, v72
	v_pk_add_f32 v[66:67], v[66:67], v[98:99]
	v_pk_add_f32 v[64:65], v[64:65], v[96:97]
	global_store_dwordx4 v[86:87], v[68:71], off offset:512
	global_store_dwordx4 v[86:87], v[64:67], off offset:528
	v_cvt_pk_bf16_f32 v72, v68, v69
	s_nop 0
	v_mul_f32_e32 v69, v69, v69
	v_fmac_f32_e32 v69, v68, v68
	v_mul_f32_e32 v68, v71, v71
	v_fmac_f32_e32 v68, v70, v70
	v_add_f32_e32 v68, v69, v68
	v_mul_f32_e32 v69, v65, v65
	v_fmac_f32_e32 v69, v64, v64
	v_add_f32_e32 v68, v68, v69
	v_mul_f32_e32 v69, v67, v67
	v_fmac_f32_e32 v69, v66, v66
	v_add_f32_e32 v68, v69, v68
	v_add_f32_e32 v68, v73, v68
	ds_swizzle_b32 v69, v68 offset:swizzle(SWAP,16)
	v_cvt_pk_bf16_f32 v73, v70, v71
	v_cvt_pk_bf16_f32 v74, v64, v65
	v_cvt_pk_bf16_f32 v75, v66, v67
	global_store_dwordx4 v[84:85], v[72:75], off offset:256 sc1
	s_waitcnt lgkmcnt(0)
	v_add_f32_e32 v64, v68, v69
	v_mov_b32_e32 v65, v64
	v_mov_b32_e32 v66, v64
	s_nop 1
	v_permlane32_swap_b32_e32 v65, v66
	s_and_saveexec_b64 s[0:1], vcc
	s_cbranch_execz .LBB0_673
	v_cmp_eq_u32_e64 s[44:45], v65, v64
	s_lshl_b32 s92, s66, 2
	s_nop 0
	v_cndmask_b32_e64 v65, v65, v66, s[44:45]
	v_add_f32_e32 v66, v64, v65
	v_lshlrev_b64 v[64:65], 6, v[112:113]
	v_lshl_add_u64 v[64:65], s[50:51], 0, v[64:65]
	v_lshl_add_u64 v[64:65], s[86:87], 2, v[64:65]
	v_lshl_add_u64 v[64:65], v[64:65], 0, s[92:93]
	global_store_dword v[64:65], v66, off
.LBB0_673:
	s_or_b64 exec, exec, s[0:1]
	v_add_u32_e32 v82, 0x80, v156
	v_ashrrev_i32_e32 v83, 31, v82
	v_lshlrev_b64 v[64:65], 12, v[82:83]
	v_lshl_add_u64 v[64:65], v[158:159], 0, v[64:65]
	global_load_dwordx4 v[84:87], v[64:65], off offset:16
	global_load_dwordx4 v[88:91], v[64:65], off
	global_load_dwordx4 v[92:95], v[64:65], off offset:528
	global_load_dwordx4 v[96:99], v[64:65], off offset:512
	v_add_u32_e32 v80, 0x90, v156
	v_ashrrev_i32_e32 v81, 31, v80
	v_lshlrev_b64 v[64:65], 12, v[80:81]
	v_lshl_add_u64 v[68:69], v[158:159], 0, v[64:65]
	global_load_dwordx4 v[72:75], v[68:69], off offset:16
	global_load_dwordx4 v[76:79], v[68:69], off
	global_load_dwordx4 v[64:67], v[68:69], off offset:528
	s_nop 0
	global_load_dwordx4 v[68:71], v[68:69], off offset:512
	v_lshlrev_b64 v[100:101], 10, v[82:83]
	v_lshl_add_u64 v[100:101], v[100:101], 0, v[154:155]
	s_waitcnt vmcnt(7)
	v_pk_add_f32 v[58:59], v[58:59], v[86:87]
	s_waitcnt vmcnt(6)
	v_pk_add_f32 v[62:63], v[62:63], v[90:91]
	v_pk_add_f32 v[60:61], v[60:61], v[88:89]
	v_lshl_add_u64 v[88:89], v[100:101], 2, s[36:37]
	v_pk_add_f32 v[56:57], v[56:57], v[84:85]
	global_store_dwordx4 v[88:89], v[60:63], off
	global_store_dwordx4 v[88:89], v[56:59], off offset:16
	v_cvt_pk_bf16_f32 v84, v60, v61
	v_cvt_pk_bf16_f32 v85, v62, v63
	v_cvt_pk_bf16_f32 v86, v56, v57
	v_lshl_add_u64 v[90:91], v[100:101], 1, s[48:49]
	v_mul_f32_e32 v61, v61, v61
	v_fmac_f32_e32 v61, v60, v60
	v_mul_f32_e32 v60, v63, v63
	v_fmac_f32_e32 v60, v62, v62
	v_mul_f32_e32 v57, v57, v57
	v_add_f32_e32 v60, v61, v60
	v_fmac_f32_e32 v57, v56, v56
	v_add_f32_e32 v56, v60, v57
	v_mul_f32_e32 v57, v59, v59
	v_fmac_f32_e32 v57, v58, v58
	s_waitcnt vmcnt(6)
	v_pk_add_f32 v[54:55], v[54:55], v[98:99]
	v_pk_add_f32 v[52:53], v[52:53], v[96:97]
	v_cvt_pk_bf16_f32 v87, v58, v59
	global_store_dwordx4 v[90:91], v[84:87], off sc1
	v_add_f32_e32 v60, v57, v56
	v_pk_add_f32 v[50:51], v[50:51], v[94:95]
	v_pk_add_f32 v[48:49], v[48:49], v[92:93]
	global_store_dwordx4 v[88:89], v[52:55], off offset:512
	global_store_dwordx4 v[88:89], v[48:51], off offset:528
	v_cvt_pk_bf16_f32 v56, v52, v53
	v_cvt_pk_bf16_f32 v57, v54, v55
	v_cvt_pk_bf16_f32 v58, v48, v49
	v_cvt_pk_bf16_f32 v59, v50, v51
	s_nop 0
	v_mul_f32_e32 v53, v53, v53
	v_fmac_f32_e32 v53, v52, v52
	v_mul_f32_e32 v52, v55, v55
	v_fmac_f32_e32 v52, v54, v54
	v_mul_f32_e32 v49, v49, v49
	v_add_f32_e32 v52, v53, v52
	v_fmac_f32_e32 v49, v48, v48
	v_add_f32_e32 v48, v52, v49
	v_mul_f32_e32 v49, v51, v51
	v_fmac_f32_e32 v49, v50, v50
	v_add_f32_e32 v48, v49, v48
	v_add_f32_e32 v48, v60, v48
	ds_swizzle_b32 v49, v48 offset:swizzle(SWAP,16)
	global_store_dwordx4 v[90:91], v[56:59], off offset:256 sc1
	s_waitcnt lgkmcnt(0)
	v_add_f32_e32 v48, v48, v49
	v_mov_b32_e32 v49, v48
	v_mov_b32_e32 v50, v48
	s_nop 1
	v_permlane32_swap_b32_e32 v49, v50
	s_and_saveexec_b64 s[0:1], vcc
	s_cbranch_execz .LBB0_675
	v_cmp_eq_u32_e64 s[44:45], v49, v48
	s_lshl_b32 s92, s66, 2
	s_nop 0
	v_cndmask_b32_e64 v49, v49, v50, s[44:45]
	v_add_f32_e32 v50, v48, v49
	v_lshlrev_b64 v[48:49], 6, v[82:83]
	v_lshl_add_u64 v[48:49], s[50:51], 0, v[48:49]
	v_lshl_add_u64 v[48:49], s[86:87], 2, v[48:49]
	v_lshl_add_u64 v[48:49], v[48:49], 0, s[92:93]
	global_store_dword v[48:49], v50, off
.LBB0_675:
	s_or_b64 exec, exec, s[0:1]
	v_lshlrev_b64 v[48:49], 10, v[80:81]
	v_lshl_add_u64 v[52:53], v[48:49], 0, v[154:155]
	s_waitcnt vmcnt(8)
	v_pk_add_f32 v[46:47], v[46:47], v[78:79]
	v_pk_add_f32 v[44:45], v[44:45], v[76:77]
	v_lshl_add_u64 v[54:55], v[52:53], 2, s[36:37]
	v_pk_add_f32 v[42:43], v[42:43], v[74:75]
	v_pk_add_f32 v[40:41], v[40:41], v[72:73]
	global_store_dwordx4 v[54:55], v[44:47], off
	global_store_dwordx4 v[54:55], v[40:43], off offset:16
	v_cvt_pk_bf16_f32 v48, v44, v45
	v_cvt_pk_bf16_f32 v49, v46, v47
	v_cvt_pk_bf16_f32 v50, v40, v41
	v_lshl_add_u64 v[52:53], v[52:53], 1, s[48:49]
	v_mul_f32_e32 v45, v45, v45
	v_fmac_f32_e32 v45, v44, v44
	v_mul_f32_e32 v44, v47, v47
	v_fmac_f32_e32 v44, v46, v46
	v_mul_f32_e32 v41, v41, v41
	v_add_f32_e32 v44, v45, v44
	v_fmac_f32_e32 v41, v40, v40
	v_add_f32_e32 v40, v44, v41
	v_mul_f32_e32 v41, v43, v43
	v_fmac_f32_e32 v41, v42, v42
	s_waitcnt vmcnt(8)
	v_pk_add_f32 v[38:39], v[38:39], v[70:71]
	v_pk_add_f32 v[36:37], v[36:37], v[68:69]
	v_cvt_pk_bf16_f32 v51, v42, v43
	global_store_dwordx4 v[52:53], v[48:51], off sc1
	v_add_f32_e32 v41, v41, v40
	v_pk_add_f32 v[34:35], v[34:35], v[66:67]
	v_pk_add_f32 v[32:33], v[32:33], v[64:65]
	global_store_dwordx4 v[54:55], v[36:39], off offset:512
	global_store_dwordx4 v[54:55], v[32:35], off offset:528
	v_cvt_pk_bf16_f32 v40, v36, v37
	s_nop 0
	v_mul_f32_e32 v37, v37, v37
	v_fmac_f32_e32 v37, v36, v36
	v_mul_f32_e32 v36, v39, v39
	v_fmac_f32_e32 v36, v38, v38
	v_add_f32_e32 v36, v37, v36
	v_mul_f32_e32 v37, v33, v33
	v_fmac_f32_e32 v37, v32, v32
	v_add_f32_e32 v36, v36, v37
	v_mul_f32_e32 v37, v35, v35
	v_fmac_f32_e32 v37, v34, v34
	v_add_f32_e32 v36, v37, v36
	v_add_f32_e32 v36, v41, v36
	ds_swizzle_b32 v37, v36 offset:swizzle(SWAP,16)
	v_cvt_pk_bf16_f32 v41, v38, v39
	v_cvt_pk_bf16_f32 v42, v32, v33
	v_cvt_pk_bf16_f32 v43, v34, v35
	global_store_dwordx4 v[52:53], v[40:43], off offset:256 sc1
	s_waitcnt lgkmcnt(0)
	v_add_f32_e32 v32, v36, v37
	v_mov_b32_e32 v33, v32
	v_mov_b32_e32 v34, v32
	s_nop 1
	v_permlane32_swap_b32_e32 v33, v34
	s_and_saveexec_b64 s[0:1], vcc
	s_cbranch_execz .LBB0_677
	v_cmp_eq_u32_e64 s[44:45], v33, v32
	s_lshl_b32 s92, s66, 2
	s_nop 0
	v_cndmask_b32_e64 v33, v33, v34, s[44:45]
	v_add_f32_e32 v34, v32, v33
	v_lshlrev_b64 v[32:33], 6, v[80:81]
	v_lshl_add_u64 v[32:33], s[50:51], 0, v[32:33]
	v_lshl_add_u64 v[32:33], s[86:87], 2, v[32:33]
	v_lshl_add_u64 v[32:33], v[32:33], 0, s[92:93]
	global_store_dword v[32:33], v34, off
.LBB0_677:
	s_or_b64 exec, exec, s[0:1]
	v_add_u32_e32 v50, 0xa0, v156
	v_ashrrev_i32_e32 v51, 31, v50
	v_lshlrev_b64 v[32:33], 12, v[50:51]
	v_lshl_add_u64 v[32:33], v[158:159], 0, v[32:33]
	global_load_dwordx4 v[52:55], v[32:33], off offset:16
	global_load_dwordx4 v[56:59], v[32:33], off
	global_load_dwordx4 v[60:63], v[32:33], off offset:528
	global_load_dwordx4 v[64:67], v[32:33], off offset:512
	v_add_u32_e32 v48, 0xb0, v156
	v_ashrrev_i32_e32 v49, 31, v48
	v_lshlrev_b64 v[32:33], 12, v[48:49]
	v_lshl_add_u64 v[36:37], v[158:159], 0, v[32:33]
	global_load_dwordx4 v[40:43], v[36:37], off offset:16
	global_load_dwordx4 v[44:47], v[36:37], off
	global_load_dwordx4 v[32:35], v[36:37], off offset:528
	s_nop 0
	global_load_dwordx4 v[36:39], v[36:37], off offset:512
	v_lshlrev_b64 v[68:69], 10, v[50:51]
	v_lshl_add_u64 v[68:69], v[68:69], 0, v[154:155]
	s_waitcnt vmcnt(7)
	v_pk_add_f32 v[26:27], v[26:27], v[54:55]
	s_waitcnt vmcnt(6)
	v_pk_add_f32 v[30:31], v[30:31], v[58:59]
	v_pk_add_f32 v[28:29], v[28:29], v[56:57]
	v_lshl_add_u64 v[56:57], v[68:69], 2, s[36:37]
	v_pk_add_f32 v[24:25], v[24:25], v[52:53]
	global_store_dwordx4 v[56:57], v[28:31], off
	global_store_dwordx4 v[56:57], v[24:27], off offset:16
	v_cvt_pk_bf16_f32 v52, v28, v29
	v_cvt_pk_bf16_f32 v53, v30, v31
	v_cvt_pk_bf16_f32 v54, v24, v25
	v_lshl_add_u64 v[58:59], v[68:69], 1, s[48:49]
	v_mul_f32_e32 v29, v29, v29
	v_fmac_f32_e32 v29, v28, v28
	v_mul_f32_e32 v28, v31, v31
	v_fmac_f32_e32 v28, v30, v30
	v_mul_f32_e32 v25, v25, v25
	v_add_f32_e32 v28, v29, v28
	v_fmac_f32_e32 v25, v24, v24
	v_add_f32_e32 v24, v28, v25
	v_mul_f32_e32 v25, v27, v27
	v_fmac_f32_e32 v25, v26, v26
	s_waitcnt vmcnt(6)
	v_pk_add_f32 v[22:23], v[22:23], v[66:67]
	v_pk_add_f32 v[20:21], v[20:21], v[64:65]
	v_cvt_pk_bf16_f32 v55, v26, v27
	global_store_dwordx4 v[58:59], v[52:55], off sc1
	v_add_f32_e32 v28, v25, v24
	v_pk_add_f32 v[18:19], v[18:19], v[62:63]
	v_pk_add_f32 v[16:17], v[16:17], v[60:61]
	global_store_dwordx4 v[56:57], v[20:23], off offset:512
	global_store_dwordx4 v[56:57], v[16:19], off offset:528
	v_cvt_pk_bf16_f32 v24, v20, v21
	v_cvt_pk_bf16_f32 v25, v22, v23
	v_cvt_pk_bf16_f32 v26, v16, v17
	v_cvt_pk_bf16_f32 v27, v18, v19
	s_nop 0
	v_mul_f32_e32 v21, v21, v21
	v_fmac_f32_e32 v21, v20, v20
	v_mul_f32_e32 v20, v23, v23
	v_fmac_f32_e32 v20, v22, v22
	v_mul_f32_e32 v17, v17, v17
	v_add_f32_e32 v20, v21, v20
	v_fmac_f32_e32 v17, v16, v16
	v_add_f32_e32 v16, v20, v17
	v_mul_f32_e32 v17, v19, v19
	v_fmac_f32_e32 v17, v18, v18
	v_add_f32_e32 v16, v17, v16
	v_add_f32_e32 v16, v28, v16
	ds_swizzle_b32 v17, v16 offset:swizzle(SWAP,16)
	global_store_dwordx4 v[58:59], v[24:27], off offset:256 sc1
	s_waitcnt lgkmcnt(0)
	v_add_f32_e32 v16, v16, v17
	v_mov_b32_e32 v17, v16
	v_mov_b32_e32 v18, v16
	s_nop 1
	v_permlane32_swap_b32_e32 v17, v18
	s_and_saveexec_b64 s[0:1], vcc
	s_cbranch_execz .LBB0_679
	v_cmp_eq_u32_e64 s[44:45], v17, v16
	s_lshl_b32 s92, s66, 2
	s_nop 0
	v_cndmask_b32_e64 v17, v17, v18, s[44:45]
	v_add_f32_e32 v18, v16, v17
	v_lshlrev_b64 v[16:17], 6, v[50:51]
	v_lshl_add_u64 v[16:17], s[50:51], 0, v[16:17]
	v_lshl_add_u64 v[16:17], s[86:87], 2, v[16:17]
	v_lshl_add_u64 v[16:17], v[16:17], 0, s[92:93]
	global_store_dword v[16:17], v18, off
.LBB0_679:
	s_or_b64 exec, exec, s[0:1]
	v_lshlrev_b64 v[16:17], 10, v[48:49]
	v_lshl_add_u64 v[20:21], v[16:17], 0, v[154:155]
	s_waitcnt vmcnt(8)
	v_pk_add_f32 v[14:15], v[14:15], v[46:47]
	v_pk_add_f32 v[12:13], v[12:13], v[44:45]
	v_lshl_add_u64 v[22:23], v[20:21], 2, s[36:37]
	v_pk_add_f32 v[10:11], v[10:11], v[42:43]
	v_pk_add_f32 v[8:9], v[8:9], v[40:41]
	global_store_dwordx4 v[22:23], v[12:15], off
	global_store_dwordx4 v[22:23], v[8:11], off offset:16
	v_cvt_pk_bf16_f32 v16, v12, v13
	v_cvt_pk_bf16_f32 v17, v14, v15
	v_cvt_pk_bf16_f32 v18, v8, v9
	v_lshl_add_u64 v[20:21], v[20:21], 1, s[48:49]
	v_mul_f32_e32 v13, v13, v13
	v_fmac_f32_e32 v13, v12, v12
	v_mul_f32_e32 v12, v15, v15
	v_fmac_f32_e32 v12, v14, v14
	v_mul_f32_e32 v9, v9, v9
	v_add_f32_e32 v12, v13, v12
	v_fmac_f32_e32 v9, v8, v8
	v_add_f32_e32 v8, v12, v9
	v_mul_f32_e32 v9, v11, v11
	v_fmac_f32_e32 v9, v10, v10
	s_waitcnt vmcnt(8)
	v_pk_add_f32 v[6:7], v[6:7], v[38:39]
	v_pk_add_f32 v[4:5], v[4:5], v[36:37]
	v_cvt_pk_bf16_f32 v19, v10, v11
	global_store_dwordx4 v[20:21], v[16:19], off sc1
	v_add_f32_e32 v9, v9, v8
	v_pk_add_f32 v[2:3], v[2:3], v[34:35]
	v_pk_add_f32 v[0:1], v[0:1], v[32:33]
	global_store_dwordx4 v[22:23], v[4:7], off offset:512
	global_store_dwordx4 v[22:23], v[0:3], off offset:528
	v_cvt_pk_bf16_f32 v8, v4, v5
	s_nop 0
	v_mul_f32_e32 v5, v5, v5
	v_fmac_f32_e32 v5, v4, v4
	v_mul_f32_e32 v4, v7, v7
	v_fmac_f32_e32 v4, v6, v6
	v_add_f32_e32 v4, v5, v4
	v_mul_f32_e32 v5, v1, v1
	v_fmac_f32_e32 v5, v0, v0
	v_add_f32_e32 v4, v4, v5
	v_mul_f32_e32 v5, v3, v3
	v_fmac_f32_e32 v5, v2, v2
	v_add_f32_e32 v4, v5, v4
	v_add_f32_e32 v4, v9, v4
	ds_swizzle_b32 v5, v4 offset:swizzle(SWAP,16)
	v_cvt_pk_bf16_f32 v9, v6, v7
	v_cvt_pk_bf16_f32 v10, v0, v1
	v_cvt_pk_bf16_f32 v11, v2, v3
	global_store_dwordx4 v[20:21], v[8:11], off offset:256 sc1
	s_waitcnt lgkmcnt(0)
	v_add_f32_e32 v0, v4, v5
	v_mov_b32_e32 v1, v0
	v_mov_b32_e32 v2, v0
	s_nop 1
	v_permlane32_swap_b32_e32 v1, v2
	s_and_saveexec_b64 s[0:1], vcc
	s_cbranch_execz .LBB0_681
	v_cmp_eq_u32_e32 vcc, v1, v0
	s_lshl_b32 s92, s66, 2
	s_nop 0
	v_cndmask_b32_e32 v1, v1, v2, vcc
	v_add_f32_e32 v2, v0, v1
	v_lshlrev_b64 v[0:1], 6, v[48:49]
	v_lshl_add_u64 v[0:1], s[50:51], 0, v[0:1]
	v_lshl_add_u64 v[0:1], s[86:87], 2, v[0:1]
	v_lshl_add_u64 v[0:1], v[0:1], 0, s[92:93]
	global_store_dword v[0:1], v2, off

.LBB0_933:
	s_lshl_b32 s0, s68, 8
	s_add_i32 s0, s0, s60
	v_mbcnt_lo_u32_b32 v182, -1, 0
	v_mbcnt_hi_u32_b32 v182, -1, v182
	s_lshl_b32 s54, s67, 2
	v_and_or_b32 v156, v182, 15, s0
	s_lshl_b32 s0, s67, 8
	v_ashrrev_i32_e32 v128, 1, v182
	s_or_b32 s0, s0, s61
	v_and_b32_e32 v128, -8, v128
	v_add_u32_e32 v154, s0, v128
	v_ashrrev_i32_e32 v155, 31, v154
	v_ashrrev_i32_e32 v157, 31, v156
	v_lshl_add_u64 v[158:159], v[154:155], 2, s[30:31]
	v_lshlrev_b64 v[128:129], 12, v[156:157]
	v_lshl_add_u64 v[174:175], v[158:159], 0, v[128:129]
	global_load_dwordx4 v[166:169], v[174:175], off
	global_load_dwordx4 v[170:173], v[174:175], off offset:16
	global_load_dwordx4 v[178:181], v[174:175], off offset:512
	global_load_dwordx4 v[186:189], v[174:175], off offset:528
	v_or_b32_e32 v160, 16, v156
	v_ashrrev_i32_e32 v161, 31, v160
	v_lshlrev_b64 v[128:129], 12, v[160:161]
	v_lshl_add_u64 v[162:163], v[158:159], 0, v[128:129]
	global_load_dwordx4 v[136:139], v[162:163], off offset:16
	global_load_dwordx4 v[140:143], v[162:163], off
	global_load_dwordx4 v[128:131], v[162:163], off offset:528
	global_load_dwordx4 v[132:135], v[162:163], off offset:512
	v_cmp_gt_u32_e32 vcc, 16, v182
	v_lshlrev_b64 v[182:183], 10, v[156:157]
	v_lshl_add_u64 v[182:183], v[182:183], 0, v[154:155]
	v_lshl_add_u64 v[182:183], v[182:183], 1, s[38:39]
	s_ashr_i32 s55, s54, 31
	s_waitcnt vmcnt(0)
	v_pk_add_f32 v[126:127], v[126:127], v[168:169]
	v_pk_add_f32 v[124:125], v[124:125], v[166:167]
	v_pk_add_f32 v[118:119], v[118:119], v[180:181]
	v_pk_add_f32 v[116:117], v[116:117], v[178:179]
	v_pk_add_f32 v[122:123], v[122:123], v[172:173]
	v_pk_add_f32 v[120:121], v[120:121], v[170:171]
	v_pk_add_f32 v[112:113], v[112:113], v[186:187]
	global_store_dwordx4 v[174:175], v[124:127], off
	global_store_dwordx4 v[174:175], v[120:123], off offset:16
	v_cvt_pk_bf16_f32 v166, v124, v125
	v_cvt_pk_bf16_f32 v167, v126, v127
	v_mul_f32_e32 v170, v117, v117
	v_mul_f32_e32 v125, v125, v125
	v_mul_f32_e32 v127, v127, v127
	v_mul_f32_e32 v171, v119, v119
	v_pk_add_f32 v[114:115], v[114:115], v[188:189]
	v_cvt_pk_bf16_f32 v168, v120, v121
	v_mul_f32_e32 v121, v121, v121
	v_mul_f32_e32 v172, v113, v113
	v_fmac_f32_e32 v125, v124, v124
	v_fmac_f32_e32 v127, v126, v126
	v_fmac_f32_e32 v170, v116, v116
	v_fmac_f32_e32 v171, v118, v118
	v_cvt_pk_bf16_f32 v169, v122, v123
	v_mul_f32_e32 v123, v123, v123
	v_mul_f32_e32 v173, v115, v115
	global_store_dwordx4 v[182:183], v[166:169], off sc1
	v_fmac_f32_e32 v121, v120, v120
	global_store_dwordx4 v[174:175], v[116:119], off offset:512
	global_store_dwordx4 v[174:175], v[112:115], off offset:528
	v_cvt_pk_bf16_f32 v120, v116, v117
	v_fmac_f32_e32 v172, v112, v112
	v_add_f32_e32 v116, v125, v127
	v_add_f32_e32 v117, v170, v171
	v_fmac_f32_e32 v123, v122, v122
	v_fmac_f32_e32 v173, v114, v114
	v_add_f32_e32 v116, v116, v121
	v_add_f32_e32 v117, v117, v172
	v_add_f32_e32 v116, v123, v116
	v_add_f32_e32 v117, v173, v117
	v_add_f32_e32 v116, v116, v117
	ds_swizzle_b32 v117, v116 offset:swizzle(SWAP,16)
	v_cvt_pk_bf16_f32 v121, v118, v119
	v_cvt_pk_bf16_f32 v122, v112, v113
	v_cvt_pk_bf16_f32 v123, v114, v115
	global_store_dwordx4 v[182:183], v[120:123], off offset:256 sc1
	s_waitcnt lgkmcnt(0)
	v_add_f32_e32 v112, v116, v117
	v_mov_b32_e32 v113, v112
	v_mov_b32_e32 v114, v112
	s_nop 1
	v_permlane32_swap_b32_e32 v113, v114
	s_and_saveexec_b64 s[0:1], vcc
	s_cbranch_execz .LBB0_935
	v_cmp_eq_u32_e64 s[42:43], v113, v112
	s_lshl_b32 s92, s57, 2
	s_nop 0
	v_cndmask_b32_e64 v113, v113, v114, s[42:43]
	v_add_f32_e32 v114, v112, v113
	v_lshlrev_b64 v[112:113], 6, v[156:157]
	v_lshl_add_u64 v[112:113], s[44:45], 0, v[112:113]
	v_lshl_add_u64 v[112:113], s[54:55], 2, v[112:113]
	v_lshl_add_u64 v[112:113], v[112:113], 0, s[92:93]
	global_store_dword v[112:113], v114, off
.LBB0_935:
	s_or_b64 exec, exec, s[0:1]
	v_lshlrev_b64 v[112:113], 10, v[160:161]
	v_pk_add_f32 v[110:111], v[110:111], v[142:143]
	v_pk_add_f32 v[108:109], v[108:109], v[140:141]
	v_lshl_add_u64 v[116:117], v[112:113], 0, v[154:155]
	v_pk_add_f32 v[106:107], v[106:107], v[138:139]
	v_pk_add_f32 v[104:105], v[104:105], v[136:137]
	global_store_dwordx4 v[162:163], v[108:111], off
	global_store_dwordx4 v[162:163], v[104:107], off offset:16
	v_cvt_pk_bf16_f32 v112, v108, v109
	v_cvt_pk_bf16_f32 v113, v110, v111
	v_cvt_pk_bf16_f32 v114, v104, v105
	v_lshl_add_u64 v[116:117], v[116:117], 1, s[38:39]
	v_mul_f32_e32 v109, v109, v109
	v_fmac_f32_e32 v109, v108, v108
	v_mul_f32_e32 v108, v111, v111
	v_fmac_f32_e32 v108, v110, v110
	v_mul_f32_e32 v105, v105, v105
	v_add_f32_e32 v108, v109, v108
	v_fmac_f32_e32 v105, v104, v104
	v_add_f32_e32 v104, v108, v105
	v_mul_f32_e32 v105, v107, v107
	v_fmac_f32_e32 v105, v106, v106
	v_pk_add_f32 v[102:103], v[102:103], v[134:135]
	v_pk_add_f32 v[100:101], v[100:101], v[132:133]
	v_cvt_pk_bf16_f32 v115, v106, v107
	global_store_dwordx4 v[116:117], v[112:115], off sc1
	v_add_f32_e32 v105, v105, v104
	v_pk_add_f32 v[98:99], v[98:99], v[130:131]
	v_pk_add_f32 v[96:97], v[96:97], v[128:129]
	global_store_dwordx4 v[162:163], v[100:103], off offset:512
	global_store_dwordx4 v[162:163], v[96:99], off offset:528
	v_cvt_pk_bf16_f32 v104, v100, v101
	s_nop 0
	v_mul_f32_e32 v101, v101, v101
	v_fmac_f32_e32 v101, v100, v100
	v_mul_f32_e32 v100, v103, v103
	v_fmac_f32_e32 v100, v102, v102
	v_add_f32_e32 v100, v101, v100
	v_mul_f32_e32 v101, v97, v97
	v_fmac_f32_e32 v101, v96, v96
	v_add_f32_e32 v100, v100, v101
	v_mul_f32_e32 v101, v99, v99
	v_fmac_f32_e32 v101, v98, v98
	v_add_f32_e32 v100, v101, v100
	v_add_f32_e32 v100, v105, v100
	ds_swizzle_b32 v101, v100 offset:swizzle(SWAP,16)
	v_cvt_pk_bf16_f32 v105, v102, v103
	v_cvt_pk_bf16_f32 v106, v96, v97
	v_cvt_pk_bf16_f32 v107, v98, v99
	global_store_dwordx4 v[116:117], v[104:107], off offset:256 sc1
	s_waitcnt lgkmcnt(0)
	v_add_f32_e32 v96, v100, v101
	v_mov_b32_e32 v97, v96
	v_mov_b32_e32 v98, v96
	s_nop 1
	v_permlane32_swap_b32_e32 v97, v98
	s_and_saveexec_b64 s[0:1], vcc
	s_cbranch_execz .LBB0_937
	v_cmp_eq_u32_e64 s[42:43], v97, v96
	s_lshl_b32 s92, s57, 2
	s_nop 0
	v_cndmask_b32_e64 v97, v97, v98, s[42:43]
	v_add_f32_e32 v98, v96, v97
	v_lshlrev_b64 v[96:97], 6, v[160:161]
	v_lshl_add_u64 v[96:97], s[44:45], 0, v[96:97]
	v_lshl_add_u64 v[96:97], s[54:55], 2, v[96:97]
	v_lshl_add_u64 v[96:97], v[96:97], 0, s[92:93]
	global_store_dword v[96:97], v98, off
.LBB0_937:
	s_or_b64 exec, exec, s[0:1]
	v_or_b32_e32 v116, 32, v156
	v_ashrrev_i32_e32 v117, 31, v116
	v_lshlrev_b64 v[96:97], 12, v[116:117]
	v_lshl_add_u64 v[134:135], v[158:159], 0, v[96:97]
	global_load_dwordx4 v[118:121], v[134:135], off
	global_load_dwordx4 v[122:125], v[134:135], off offset:16
	global_load_dwordx4 v[126:129], v[134:135], off offset:512
	global_load_dwordx4 v[130:133], v[134:135], off offset:528
	v_or_b32_e32 v112, 48, v156
	v_ashrrev_i32_e32 v113, 31, v112
	v_lshlrev_b64 v[96:97], 12, v[112:113]
	v_lshl_add_u64 v[114:115], v[158:159], 0, v[96:97]
	global_load_dwordx4 v[104:107], v[114:115], off offset:16
	global_load_dwordx4 v[108:111], v[114:115], off
	global_load_dwordx4 v[96:99], v[114:115], off offset:528
	global_load_dwordx4 v[100:103], v[114:115], off offset:512
	v_lshlrev_b64 v[136:137], 10, v[116:117]
	v_lshl_add_u64 v[136:137], v[136:137], 0, v[154:155]
	v_lshl_add_u64 v[136:137], v[136:137], 1, s[38:39]
	s_waitcnt vmcnt(7)
	v_pk_add_f32 v[94:95], v[94:95], v[120:121]
	v_pk_add_f32 v[92:93], v[92:93], v[118:119]
	s_waitcnt vmcnt(5)
	v_pk_add_f32 v[86:87], v[86:87], v[128:129]
	v_pk_add_f32 v[84:85], v[84:85], v[126:127]
	v_pk_add_f32 v[90:91], v[90:91], v[124:125]
	v_pk_add_f32 v[88:89], v[88:89], v[122:123]
	s_waitcnt vmcnt(4)
	v_pk_add_f32 v[80:81], v[80:81], v[130:131]
	global_store_dwordx4 v[134:135], v[92:95], off
	global_store_dwordx4 v[134:135], v[88:91], off offset:16
	v_cvt_pk_bf16_f32 v118, v92, v93
	v_cvt_pk_bf16_f32 v119, v94, v95
	v_mul_f32_e32 v122, v85, v85
	v_mul_f32_e32 v93, v93, v93
	v_mul_f32_e32 v95, v95, v95
	v_mul_f32_e32 v123, v87, v87
	v_pk_add_f32 v[82:83], v[82:83], v[132:133]
	v_cvt_pk_bf16_f32 v120, v88, v89
	v_mul_f32_e32 v89, v89, v89
	v_mul_f32_e32 v124, v81, v81
	v_fmac_f32_e32 v93, v92, v92
	v_fmac_f32_e32 v95, v94, v94
	v_fmac_f32_e32 v122, v84, v84
	v_fmac_f32_e32 v123, v86, v86
	v_cvt_pk_bf16_f32 v121, v90, v91
	v_mul_f32_e32 v91, v91, v91
	v_mul_f32_e32 v125, v83, v83
	global_store_dwordx4 v[136:137], v[118:121], off sc1
	v_fmac_f32_e32 v89, v88, v88
	global_store_dwordx4 v[134:135], v[84:87], off offset:512
	global_store_dwordx4 v[134:135], v[80:83], off offset:528
	v_cvt_pk_bf16_f32 v88, v84, v85
	v_fmac_f32_e32 v124, v80, v80
	v_add_f32_e32 v84, v93, v95
	v_add_f32_e32 v85, v122, v123
	v_fmac_f32_e32 v91, v90, v90
	v_fmac_f32_e32 v125, v82, v82
	v_add_f32_e32 v84, v84, v89
	v_add_f32_e32 v85, v85, v124
	v_add_f32_e32 v84, v91, v84
	v_add_f32_e32 v85, v125, v85
	v_add_f32_e32 v84, v84, v85
	ds_swizzle_b32 v85, v84 offset:swizzle(SWAP,16)
	v_cvt_pk_bf16_f32 v89, v86, v87
	v_cvt_pk_bf16_f32 v90, v80, v81
	v_cvt_pk_bf16_f32 v91, v82, v83
	global_store_dwordx4 v[136:137], v[88:91], off offset:256 sc1
	s_waitcnt lgkmcnt(0)
	v_add_f32_e32 v80, v84, v85
	v_mov_b32_e32 v81, v80
	v_mov_b32_e32 v82, v80
	s_nop 1
	v_permlane32_swap_b32_e32 v81, v82
	s_and_saveexec_b64 s[0:1], vcc
	s_cbranch_execz .LBB0_939
	v_cmp_eq_u32_e64 s[42:43], v81, v80
	s_lshl_b32 s92, s57, 2
	s_nop 0
	v_cndmask_b32_e64 v81, v81, v82, s[42:43]
	v_add_f32_e32 v82, v80, v81
	v_lshlrev_b64 v[80:81], 6, v[116:117]
	v_lshl_add_u64 v[80:81], s[44:45], 0, v[80:81]
	v_lshl_add_u64 v[80:81], s[54:55], 2, v[80:81]
	v_lshl_add_u64 v[80:81], v[80:81], 0, s[92:93]
	global_store_dword v[80:81], v82, off
.LBB0_939:
	s_or_b64 exec, exec, s[0:1]
	v_lshlrev_b64 v[80:81], 10, v[112:113]
	s_waitcnt vmcnt(8)
	v_pk_add_f32 v[78:79], v[78:79], v[110:111]
	v_pk_add_f32 v[76:77], v[76:77], v[108:109]
	v_lshl_add_u64 v[84:85], v[80:81], 0, v[154:155]
	v_pk_add_f32 v[74:75], v[74:75], v[106:107]
	v_pk_add_f32 v[72:73], v[72:73], v[104:105]
	global_store_dwordx4 v[114:115], v[76:79], off
	global_store_dwordx4 v[114:115], v[72:75], off offset:16
	v_cvt_pk_bf16_f32 v80, v76, v77
	v_cvt_pk_bf16_f32 v81, v78, v79
	v_cvt_pk_bf16_f32 v82, v72, v73
	v_lshl_add_u64 v[84:85], v[84:85], 1, s[38:39]
	v_mul_f32_e32 v77, v77, v77
	v_fmac_f32_e32 v77, v76, v76
	v_mul_f32_e32 v76, v79, v79
	v_fmac_f32_e32 v76, v78, v78
	v_mul_f32_e32 v73, v73, v73
	v_add_f32_e32 v76, v77, v76
	v_fmac_f32_e32 v73, v72, v72
	v_add_f32_e32 v72, v76, v73
	v_mul_f32_e32 v73, v75, v75
	v_fmac_f32_e32 v73, v74, v74
	s_waitcnt vmcnt(8)
	v_pk_add_f32 v[70:71], v[70:71], v[102:103]
	v_pk_add_f32 v[68:69], v[68:69], v[100:101]
	v_cvt_pk_bf16_f32 v83, v74, v75
	global_store_dwordx4 v[84:85], v[80:83], off sc1
	v_add_f32_e32 v73, v73, v72
	v_pk_add_f32 v[66:67], v[66:67], v[98:99]
	v_pk_add_f32 v[64:65], v[64:65], v[96:97]
	global_store_dwordx4 v[114:115], v[68:71], off offset:512
	global_store_dwordx4 v[114:115], v[64:67], off offset:528
	v_cvt_pk_bf16_f32 v72, v68, v69
	s_nop 0
	v_mul_f32_e32 v69, v69, v69
	v_fmac_f32_e32 v69, v68, v68
	v_mul_f32_e32 v68, v71, v71
	v_fmac_f32_e32 v68, v70, v70
	v_add_f32_e32 v68, v69, v68
	v_mul_f32_e32 v69, v65, v65
	v_fmac_f32_e32 v69, v64, v64
	v_add_f32_e32 v68, v68, v69
	v_mul_f32_e32 v69, v67, v67
	v_fmac_f32_e32 v69, v66, v66
	v_add_f32_e32 v68, v69, v68
	v_add_f32_e32 v68, v73, v68
	ds_swizzle_b32 v69, v68 offset:swizzle(SWAP,16)
	v_cvt_pk_bf16_f32 v73, v70, v71
	v_cvt_pk_bf16_f32 v74, v64, v65
	v_cvt_pk_bf16_f32 v75, v66, v67
	global_store_dwordx4 v[84:85], v[72:75], off offset:256 sc1
	s_waitcnt lgkmcnt(0)
	v_add_f32_e32 v64, v68, v69
	v_mov_b32_e32 v65, v64
	v_mov_b32_e32 v66, v64
	s_nop 1
	v_permlane32_swap_b32_e32 v65, v66
	s_and_saveexec_b64 s[0:1], vcc
	s_cbranch_execz .LBB0_941
	v_cmp_eq_u32_e64 s[42:43], v65, v64
	s_lshl_b32 s92, s57, 2
	s_nop 0
	v_cndmask_b32_e64 v65, v65, v66, s[42:43]
	v_add_f32_e32 v66, v64, v65
	v_lshlrev_b64 v[64:65], 6, v[112:113]
	v_lshl_add_u64 v[64:65], s[44:45], 0, v[64:65]
	v_lshl_add_u64 v[64:65], s[54:55], 2, v[64:65]
	v_lshl_add_u64 v[64:65], v[64:65], 0, s[92:93]
	global_store_dword v[64:65], v66, off
.LBB0_941:
	s_or_b64 exec, exec, s[0:1]
	v_add_u32_e32 v84, 0x80, v156
	v_ashrrev_i32_e32 v85, 31, v84
	v_lshlrev_b64 v[64:65], 12, v[84:85]
	v_lshl_add_u64 v[102:103], v[158:159], 0, v[64:65]
	global_load_dwordx4 v[86:89], v[102:103], off
	global_load_dwordx4 v[90:93], v[102:103], off offset:16
	global_load_dwordx4 v[94:97], v[102:103], off offset:512
	global_load_dwordx4 v[98:101], v[102:103], off offset:528
	v_add_u32_e32 v80, 0x90, v156
	v_ashrrev_i32_e32 v81, 31, v80
	v_lshlrev_b64 v[64:65], 12, v[80:81]
	v_lshl_add_u64 v[82:83], v[158:159], 0, v[64:65]
	global_load_dwordx4 v[72:75], v[82:83], off offset:16
	global_load_dwordx4 v[76:79], v[82:83], off
	global_load_dwordx4 v[64:67], v[82:83], off offset:528
	global_load_dwordx4 v[68:71], v[82:83], off offset:512
	v_lshlrev_b64 v[104:105], 10, v[84:85]
	v_lshl_add_u64 v[104:105], v[104:105], 0, v[154:155]
	v_lshl_add_u64 v[104:105], v[104:105], 1, s[38:39]
	s_waitcnt vmcnt(7)
	v_pk_add_f32 v[62:63], v[62:63], v[88:89]
	v_pk_add_f32 v[60:61], v[60:61], v[86:87]
	s_waitcnt vmcnt(5)
	v_pk_add_f32 v[54:55], v[54:55], v[96:97]
	v_pk_add_f32 v[52:53], v[52:53], v[94:95]
	v_pk_add_f32 v[58:59], v[58:59], v[92:93]
	v_pk_add_f32 v[56:57], v[56:57], v[90:91]
	s_waitcnt vmcnt(4)
	v_pk_add_f32 v[48:49], v[48:49], v[98:99]
	global_store_dwordx4 v[102:103], v[60:63], off
	global_store_dwordx4 v[102:103], v[56:59], off offset:16
	v_cvt_pk_bf16_f32 v86, v60, v61
	v_cvt_pk_bf16_f32 v87, v62, v63
	v_mul_f32_e32 v90, v53, v53
	v_mul_f32_e32 v61, v61, v61
	v_mul_f32_e32 v63, v63, v63
	v_mul_f32_e32 v91, v55, v55
	v_pk_add_f32 v[50:51], v[50:51], v[100:101]
	v_cvt_pk_bf16_f32 v88, v56, v57
	v_mul_f32_e32 v57, v57, v57
	v_mul_f32_e32 v92, v49, v49
	v_fmac_f32_e32 v61, v60, v60
	v_fmac_f32_e32 v63, v62, v62
	v_fmac_f32_e32 v90, v52, v52
	v_fmac_f32_e32 v91, v54, v54
	v_cvt_pk_bf16_f32 v89, v58, v59
	v_mul_f32_e32 v59, v59, v59
	v_mul_f32_e32 v93, v51, v51
	global_store_dwordx4 v[104:105], v[86:89], off sc1
	v_fmac_f32_e32 v57, v56, v56
	global_store_dwordx4 v[102:103], v[52:55], off offset:512
	global_store_dwordx4 v[102:103], v[48:51], off offset:528
	v_cvt_pk_bf16_f32 v56, v52, v53
	v_fmac_f32_e32 v92, v48, v48
	v_add_f32_e32 v52, v61, v63
	v_add_f32_e32 v53, v90, v91
	v_fmac_f32_e32 v59, v58, v58
	v_fmac_f32_e32 v93, v50, v50
	v_add_f32_e32 v52, v52, v57
	v_add_f32_e32 v53, v53, v92
	v_add_f32_e32 v52, v59, v52
	v_add_f32_e32 v53, v93, v53
	v_add_f32_e32 v52, v52, v53
	ds_swizzle_b32 v53, v52 offset:swizzle(SWAP,16)
	v_cvt_pk_bf16_f32 v57, v54, v55
	v_cvt_pk_bf16_f32 v58, v48, v49
	v_cvt_pk_bf16_f32 v59, v50, v51
	global_store_dwordx4 v[104:105], v[56:59], off offset:256 sc1
	s_waitcnt lgkmcnt(0)
	v_add_f32_e32 v48, v52, v53
	v_mov_b32_e32 v49, v48
	v_mov_b32_e32 v50, v48
	s_nop 1
	v_permlane32_swap_b32_e32 v49, v50
	s_and_saveexec_b64 s[0:1], vcc
	s_cbranch_execz .LBB0_943
	v_cmp_eq_u32_e64 s[42:43], v49, v48
	s_lshl_b32 s92, s57, 2
	s_nop 0
	v_cndmask_b32_e64 v49, v49, v50, s[42:43]
	v_add_f32_e32 v50, v48, v49
	v_lshlrev_b64 v[48:49], 6, v[84:85]
	v_lshl_add_u64 v[48:49], s[44:45], 0, v[48:49]
	v_lshl_add_u64 v[48:49], s[54:55], 2, v[48:49]
	v_lshl_add_u64 v[48:49], v[48:49], 0, s[92:93]
	global_store_dword v[48:49], v50, off
.LBB0_943:
	s_or_b64 exec, exec, s[0:1]
	v_lshlrev_b64 v[48:49], 10, v[80:81]
	s_waitcnt vmcnt(8)
	v_pk_add_f32 v[46:47], v[46:47], v[78:79]
	v_pk_add_f32 v[44:45], v[44:45], v[76:77]
	v_lshl_add_u64 v[52:53], v[48:49], 0, v[154:155]
	v_pk_add_f32 v[42:43], v[42:43], v[74:75]
	v_pk_add_f32 v[40:41], v[40:41], v[72:73]
	global_store_dwordx4 v[82:83], v[44:47], off
	global_store_dwordx4 v[82:83], v[40:43], off offset:16
	v_cvt_pk_bf16_f32 v48, v44, v45
	v_cvt_pk_bf16_f32 v49, v46, v47
	v_cvt_pk_bf16_f32 v50, v40, v41
	v_lshl_add_u64 v[52:53], v[52:53], 1, s[38:39]
	v_mul_f32_e32 v45, v45, v45
	v_fmac_f32_e32 v45, v44, v44
	v_mul_f32_e32 v44, v47, v47
	v_fmac_f32_e32 v44, v46, v46
	v_mul_f32_e32 v41, v41, v41
	v_add_f32_e32 v44, v45, v44
	v_fmac_f32_e32 v41, v40, v40
	v_add_f32_e32 v40, v44, v41
	v_mul_f32_e32 v41, v43, v43
	v_fmac_f32_e32 v41, v42, v42
	s_waitcnt vmcnt(8)
	v_pk_add_f32 v[38:39], v[38:39], v[70:71]
	v_pk_add_f32 v[36:37], v[36:37], v[68:69]
	v_cvt_pk_bf16_f32 v51, v42, v43
	global_store_dwordx4 v[52:53], v[48:51], off sc1
	v_add_f32_e32 v41, v41, v40
	v_pk_add_f32 v[34:35], v[34:35], v[66:67]
	v_pk_add_f32 v[32:33], v[32:33], v[64:65]
	global_store_dwordx4 v[82:83], v[36:39], off offset:512
	global_store_dwordx4 v[82:83], v[32:35], off offset:528
	v_cvt_pk_bf16_f32 v40, v36, v37
	s_nop 0
	v_mul_f32_e32 v37, v37, v37
	v_fmac_f32_e32 v37, v36, v36
	v_mul_f32_e32 v36, v39, v39
	v_fmac_f32_e32 v36, v38, v38
	v_add_f32_e32 v36, v37, v36
	v_mul_f32_e32 v37, v33, v33
	v_fmac_f32_e32 v37, v32, v32
	v_add_f32_e32 v36, v36, v37
	v_mul_f32_e32 v37, v35, v35
	v_fmac_f32_e32 v37, v34, v34
	v_add_f32_e32 v36, v37, v36
	v_add_f32_e32 v36, v41, v36
	ds_swizzle_b32 v37, v36 offset:swizzle(SWAP,16)
	v_cvt_pk_bf16_f32 v41, v38, v39
	v_cvt_pk_bf16_f32 v42, v32, v33
	v_cvt_pk_bf16_f32 v43, v34, v35
	global_store_dwordx4 v[52:53], v[40:43], off offset:256 sc1
	s_waitcnt lgkmcnt(0)
	v_add_f32_e32 v32, v36, v37
	v_mov_b32_e32 v33, v32
	v_mov_b32_e32 v34, v32
	s_nop 1
	v_permlane32_swap_b32_e32 v33, v34
	s_and_saveexec_b64 s[0:1], vcc
	s_cbranch_execz .LBB0_945
	v_cmp_eq_u32_e64 s[42:43], v33, v32
	s_lshl_b32 s92, s57, 2
	s_nop 0
	v_cndmask_b32_e64 v33, v33, v34, s[42:43]
	v_add_f32_e32 v34, v32, v33
	v_lshlrev_b64 v[32:33], 6, v[80:81]
	v_lshl_add_u64 v[32:33], s[44:45], 0, v[32:33]
	v_lshl_add_u64 v[32:33], s[54:55], 2, v[32:33]
	v_lshl_add_u64 v[32:33], v[32:33], 0, s[92:93]
	global_store_dword v[32:33], v34, off
.LBB0_945:
	s_or_b64 exec, exec, s[0:1]
	v_add_u32_e32 v52, 0xa0, v156
	v_ashrrev_i32_e32 v53, 31, v52
	v_lshlrev_b64 v[32:33], 12, v[52:53]
	v_lshl_add_u64 v[70:71], v[158:159], 0, v[32:33]
	global_load_dwordx4 v[54:57], v[70:71], off
	global_load_dwordx4 v[58:61], v[70:71], off offset:16
	global_load_dwordx4 v[62:65], v[70:71], off offset:512
	global_load_dwordx4 v[66:69], v[70:71], off offset:528
	v_add_u32_e32 v48, 0xb0, v156
	v_ashrrev_i32_e32 v49, 31, v48
	v_lshlrev_b64 v[32:33], 12, v[48:49]
	v_lshl_add_u64 v[50:51], v[158:159], 0, v[32:33]
	global_load_dwordx4 v[40:43], v[50:51], off offset:16
	global_load_dwordx4 v[44:47], v[50:51], off
	global_load_dwordx4 v[32:35], v[50:51], off offset:528
	global_load_dwordx4 v[36:39], v[50:51], off offset:512
	v_lshlrev_b64 v[72:73], 10, v[52:53]
	v_lshl_add_u64 v[72:73], v[72:73], 0, v[154:155]
	v_lshl_add_u64 v[72:73], v[72:73], 1, s[38:39]
	s_waitcnt vmcnt(7)
	v_pk_add_f32 v[30:31], v[30:31], v[56:57]
	v_pk_add_f32 v[28:29], v[28:29], v[54:55]
	s_waitcnt vmcnt(5)
	v_pk_add_f32 v[22:23], v[22:23], v[64:65]
	v_pk_add_f32 v[20:21], v[20:21], v[62:63]
	v_pk_add_f32 v[26:27], v[26:27], v[60:61]
	v_pk_add_f32 v[24:25], v[24:25], v[58:59]
	s_waitcnt vmcnt(4)
	v_pk_add_f32 v[16:17], v[16:17], v[66:67]
	global_store_dwordx4 v[70:71], v[28:31], off
	global_store_dwordx4 v[70:71], v[24:27], off offset:16
	v_cvt_pk_bf16_f32 v54, v28, v29
	v_cvt_pk_bf16_f32 v55, v30, v31
	v_mul_f32_e32 v58, v21, v21
	v_mul_f32_e32 v29, v29, v29
	v_mul_f32_e32 v31, v31, v31
	v_mul_f32_e32 v59, v23, v23
	v_pk_add_f32 v[18:19], v[18:19], v[68:69]
	v_cvt_pk_bf16_f32 v56, v24, v25
	v_mul_f32_e32 v25, v25, v25
	v_mul_f32_e32 v60, v17, v17
	v_fmac_f32_e32 v29, v28, v28
	v_fmac_f32_e32 v31, v30, v30
	v_fmac_f32_e32 v58, v20, v20
	v_fmac_f32_e32 v59, v22, v22
	v_cvt_pk_bf16_f32 v57, v26, v27
	v_mul_f32_e32 v27, v27, v27
	v_mul_f32_e32 v61, v19, v19
	global_store_dwordx4 v[72:73], v[54:57], off sc1
	v_fmac_f32_e32 v25, v24, v24
	global_store_dwordx4 v[70:71], v[20:23], off offset:512
	global_store_dwordx4 v[70:71], v[16:19], off offset:528
	v_cvt_pk_bf16_f32 v24, v20, v21
	v_fmac_f32_e32 v60, v16, v16
	v_add_f32_e32 v20, v29, v31
	v_add_f32_e32 v21, v58, v59
	v_fmac_f32_e32 v27, v26, v26
	v_fmac_f32_e32 v61, v18, v18
	v_add_f32_e32 v20, v20, v25
	v_add_f32_e32 v21, v21, v60
	v_add_f32_e32 v20, v27, v20
	v_add_f32_e32 v21, v61, v21
	v_add_f32_e32 v20, v20, v21
	ds_swizzle_b32 v21, v20 offset:swizzle(SWAP,16)
	v_cvt_pk_bf16_f32 v25, v22, v23
	v_cvt_pk_bf16_f32 v26, v16, v17
	v_cvt_pk_bf16_f32 v27, v18, v19
	global_store_dwordx4 v[72:73], v[24:27], off offset:256 sc1
	s_waitcnt lgkmcnt(0)
	v_add_f32_e32 v16, v20, v21
	v_mov_b32_e32 v17, v16
	v_mov_b32_e32 v18, v16
	s_nop 1
	v_permlane32_swap_b32_e32 v17, v18
	s_and_saveexec_b64 s[0:1], vcc
	s_cbranch_execz .LBB0_947
	v_cmp_eq_u32_e64 s[42:43], v17, v16
	s_lshl_b32 s92, s57, 2
	s_nop 0
	v_cndmask_b32_e64 v17, v17, v18, s[42:43]
	v_add_f32_e32 v18, v16, v17
	v_lshlrev_b64 v[16:17], 6, v[52:53]
	v_lshl_add_u64 v[16:17], s[44:45], 0, v[16:17]
	v_lshl_add_u64 v[16:17], s[54:55], 2, v[16:17]
	v_lshl_add_u64 v[16:17], v[16:17], 0, s[92:93]
	global_store_dword v[16:17], v18, off
.LBB0_947:
	s_or_b64 exec, exec, s[0:1]
	v_lshlrev_b64 v[16:17], 10, v[48:49]
	s_waitcnt vmcnt(8)
	v_pk_add_f32 v[14:15], v[14:15], v[46:47]
	v_pk_add_f32 v[12:13], v[12:13], v[44:45]
	v_lshl_add_u64 v[20:21], v[16:17], 0, v[154:155]
	v_pk_add_f32 v[10:11], v[10:11], v[42:43]
	v_pk_add_f32 v[8:9], v[8:9], v[40:41]
	global_store_dwordx4 v[50:51], v[12:15], off
	global_store_dwordx4 v[50:51], v[8:11], off offset:16
	v_cvt_pk_bf16_f32 v16, v12, v13
	v_cvt_pk_bf16_f32 v17, v14, v15
	v_cvt_pk_bf16_f32 v18, v8, v9
	v_lshl_add_u64 v[20:21], v[20:21], 1, s[38:39]
	v_mul_f32_e32 v13, v13, v13
	v_fmac_f32_e32 v13, v12, v12
	v_mul_f32_e32 v12, v15, v15
	v_fmac_f32_e32 v12, v14, v14
	v_mul_f32_e32 v9, v9, v9
	v_add_f32_e32 v12, v13, v12
	v_fmac_f32_e32 v9, v8, v8
	v_add_f32_e32 v8, v12, v9
	v_mul_f32_e32 v9, v11, v11
	v_fmac_f32_e32 v9, v10, v10
	s_waitcnt vmcnt(8)
	v_pk_add_f32 v[6:7], v[6:7], v[38:39]
	v_pk_add_f32 v[4:5], v[4:5], v[36:37]
	v_cvt_pk_bf16_f32 v19, v10, v11
	global_store_dwordx4 v[20:21], v[16:19], off sc1
	v_add_f32_e32 v9, v9, v8
	v_pk_add_f32 v[2:3], v[2:3], v[34:35]
	v_pk_add_f32 v[0:1], v[0:1], v[32:33]
	global_store_dwordx4 v[50:51], v[4:7], off offset:512
	global_store_dwordx4 v[50:51], v[0:3], off offset:528
	v_cvt_pk_bf16_f32 v8, v4, v5
	s_nop 0
	v_mul_f32_e32 v5, v5, v5
	v_fmac_f32_e32 v5, v4, v4
	v_mul_f32_e32 v4, v7, v7
	v_fmac_f32_e32 v4, v6, v6
	v_add_f32_e32 v4, v5, v4
	v_mul_f32_e32 v5, v1, v1
	v_fmac_f32_e32 v5, v0, v0
	v_add_f32_e32 v4, v4, v5
	v_mul_f32_e32 v5, v3, v3
	v_fmac_f32_e32 v5, v2, v2
	v_add_f32_e32 v4, v5, v4
	v_add_f32_e32 v4, v9, v4
	ds_swizzle_b32 v5, v4 offset:swizzle(SWAP,16)
	v_cvt_pk_bf16_f32 v9, v6, v7
	v_cvt_pk_bf16_f32 v10, v0, v1
	v_cvt_pk_bf16_f32 v11, v2, v3
	global_store_dwordx4 v[20:21], v[8:11], off offset:256 sc1
	s_waitcnt lgkmcnt(0)
	v_add_f32_e32 v0, v4, v5
	v_mov_b32_e32 v1, v0
	v_mov_b32_e32 v2, v0
	s_nop 1
	v_permlane32_swap_b32_e32 v1, v2
	s_and_saveexec_b64 s[0:1], vcc
	s_cbranch_execz .LBB0_949
	v_cmp_eq_u32_e32 vcc, v1, v0
	s_lshl_b32 s92, s57, 2
	s_nop 0
	v_cndmask_b32_e32 v1, v1, v2, vcc
	v_add_f32_e32 v2, v0, v1
	v_lshlrev_b64 v[0:1], 6, v[48:49]
	v_lshl_add_u64 v[0:1], s[44:45], 0, v[0:1]
	v_lshl_add_u64 v[0:1], s[54:55], 2, v[0:1]
	v_lshl_add_u64 v[0:1], v[0:1], 0, s[92:93]
	global_store_dword v[0:1], v2, off
